# prep-phase stores write-through (sc1): consumers are other XCDs, barrier write-back has nothing to flush
# baseline (speedup 1.0000x reference)
.LBB0_19:
	s_waitcnt lgkmcnt(0)
	s_barrier
	ds_read2_b32 v[18:19], v15 offset1:65
	s_ashr_i32 s5, s4, 31
	s_lshr_b32 s5, s5, 26
	s_add_i32 s5, s4, s5
	ds_read2_b32 v[20:21], v15 offset0:130 offset1:195
	s_waitcnt lgkmcnt(1)
	v_cvt_f16_f32_e32 v11, v18
	v_add_u32_e32 v18, 0x400, v15
	ds_read2_b32 v[22:23], v18 offset0:4 offset1:69
	s_ashr_i32 s6, s5, 6
	s_and_b32 s5, s5, 0xffc0
	s_sub_i32 s4, s4, s5
	s_bfe_i32 s5, s4, 0x80000
	s_bfe_u32 s5, s5, 0x3000c
	v_cvt_f16_f32_sdwa v24, v19 dst_sel:WORD_1 dst_unused:UNUSED_PAD src0_sel:DWORD
	ds_read2_b32 v[18:19], v18 offset0:134 offset1:199
	s_add_i32 s5, s4, s5
	s_waitcnt lgkmcnt(2)
	v_cvt_f16_f32_e32 v20, v20
	v_cvt_f16_f32_sdwa v21, v21 dst_sel:WORD_1 dst_unused:UNUSED_PAD src0_sel:DWORD
	s_waitcnt lgkmcnt(1)
	v_cvt_f16_f32_e32 v22, v22
	v_cvt_f16_f32_sdwa v23, v23 dst_sel:WORD_1 dst_unused:UNUSED_PAD src0_sel:DWORD
	s_bfe_i32 s7, s5, 0x80000
	s_and_b32 s5, s5, 0xf8
	s_sub_i32 s4, s4, s5
	s_sext_i32_i16 s8, s7
	s_sext_i32_i8 s9, s4
	s_ashr_i32 s7, s6, 31
	s_lshl_b64 s[4:5], s[6:7], 19
	s_waitcnt lgkmcnt(0)
	v_cvt_f16_f32_sdwa v26, v19 dst_sel:WORD_1 dst_unused:UNUSED_PAD src0_sel:DWORD
	v_or_b32_e32 v19, v21, v20
	v_or_b32_e32 v20, v23, v22
	v_lshl_add_u32 v22, s9, 6, v14
	s_add_u32 s4, s3, s4
	v_ashrrev_i32_e32 v23, 31, v22
	s_addc_u32 s5, s28, s5
	v_lshlrev_b64 v[22:23], 10, v[22:23]
	v_cvt_f16_f32_e32 v25, v18
	v_lshl_add_u64 v[22:23], s[4:5], 0, v[22:23]
	s_lshl_b32 s4, s8, 3
	s_andn2_b32 s4, s4, 63
	s_ashr_i32 s5, s4, 31
	v_lshl_add_u64 v[22:23], s[4:5], 1, v[22:23]
	v_or_b32_e32 v18, v24, v11
	v_or_b32_e32 v21, v26, v25
	v_lshl_add_u64 v[22:23], v[22:23], 0, v[8:9]
	s_andn2_b64 vcc, exec, s[0:1]
	s_mov_b32 s4, s2
	global_store_dwordx4 v[22:23], v[18:21], off sc1
	s_barrier
	s_cbranch_vccz .LBB0_22

.LBB0_31:
	s_or_b64 exec, exec, s[12:13]
	s_waitcnt vmcnt(1)
	v_cvt_f16_f32_e32 v32, v24
	v_cvt_f16_f32_sdwa v35, v25 dst_sel:WORD_1 dst_unused:UNUSED_PAD src0_sel:DWORD
	s_waitcnt vmcnt(0)
	v_cvt_f16_f32_e32 v28, v28
	v_cvt_f16_f32_sdwa v29, v29 dst_sel:WORD_1 dst_unused:UNUSED_PAD src0_sel:DWORD
	v_cvt_f16_f32_e32 v30, v30
	v_cvt_f16_f32_sdwa v31, v31 dst_sel:WORD_1 dst_unused:UNUSED_PAD src0_sel:DWORD
	v_cvt_f16_f32_e32 v37, v26
	v_cvt_f16_f32_sdwa v27, v27 dst_sel:WORD_1 dst_unused:UNUSED_PAD src0_sel:DWORD
	v_or_b32_e32 v26, v35, v32
	v_ashrrev_i32_e32 v35, 31, v34
	v_or_b32_e32 v24, v29, v28
	v_or_b32_e32 v25, v31, v30
	v_or_b32_e32 v27, v27, v37
	v_lshl_add_u64 v[28:29], v[34:35], 4, s[6:7]
	global_store_dwordx4 v[28:29], v[24:27], off sc1
	s_and_saveexec_b64 s[12:13], vcc
	s_cbranch_execnz .LBB0_34
	s_or_b64 exec, exec, s[12:13]
	s_and_saveexec_b64 s[12:13], s[4:5]
	s_cbranch_execnz .LBB0_35

.LBB0_34:
	v_cvt_f16_f32_e32 v24, v0
	v_cvt_f16_f32_sdwa v25, v1 dst_sel:WORD_1 dst_unused:UNUSED_PAD src0_sel:DWORD
	v_cvt_f16_f32_e32 v26, v2
	v_cvt_f16_f32_sdwa v27, v3 dst_sel:WORD_1 dst_unused:UNUSED_PAD src0_sel:DWORD
	v_cvt_f16_f32_e32 v28, v8
	v_cvt_f16_f32_sdwa v29, v9 dst_sel:WORD_1 dst_unused:UNUSED_PAD src0_sel:DWORD
	v_cvt_f16_f32_e32 v30, v10
	v_cvt_f16_f32_sdwa v31, v11 dst_sel:WORD_1 dst_unused:UNUSED_PAD src0_sel:DWORD
	v_ashrrev_i32_e32 v37, 31, v36
	v_or_b32_e32 v24, v25, v24
	v_or_b32_e32 v25, v27, v26
	v_or_b32_e32 v26, v29, v28
	v_or_b32_e32 v27, v31, v30
	v_lshl_add_u64 v[28:29], v[36:37], 4, s[6:7]
	global_store_dwordx4 v[28:29], v[24:27], off sc1
	s_or_b64 exec, exec, s[12:13]
	s_and_saveexec_b64 s[12:13], s[4:5]
	s_cbranch_execz .LBB0_33
.LBB0_35:
	v_cvt_f16_f32_e32 v24, v4
	v_cvt_f16_f32_sdwa v25, v5 dst_sel:WORD_1 dst_unused:UNUSED_PAD src0_sel:DWORD
	v_cvt_f16_f32_e32 v26, v6
	v_cvt_f16_f32_sdwa v27, v7 dst_sel:WORD_1 dst_unused:UNUSED_PAD src0_sel:DWORD
	v_cvt_f16_f32_e32 v28, v16
	v_cvt_f16_f32_sdwa v29, v17 dst_sel:WORD_1 dst_unused:UNUSED_PAD src0_sel:DWORD
	v_cvt_f16_f32_e32 v30, v18
	v_cvt_f16_f32_sdwa v31, v19 dst_sel:WORD_1 dst_unused:UNUSED_PAD src0_sel:DWORD
	v_ashrrev_i32_e32 v39, 31, v38
	v_or_b32_e32 v24, v25, v24
	v_or_b32_e32 v25, v27, v26
	v_or_b32_e32 v26, v29, v28
	v_or_b32_e32 v27, v31, v30
	v_lshl_add_u64 v[28:29], v[38:39], 4, s[6:7]
	global_store_dwordx4 v[28:29], v[24:27], off sc1
	s_or_b64 exec, exec, s[12:13]
	s_and_saveexec_b64 s[4:5], s[0:1]
	s_cbranch_execz .LBB0_24
.LBB0_36:
	v_cvt_f16_f32_e32 v24, v12
	v_cvt_f16_f32_sdwa v25, v13 dst_sel:WORD_1 dst_unused:UNUSED_PAD src0_sel:DWORD
	v_cvt_f16_f32_e32 v26, v14
	v_cvt_f16_f32_sdwa v27, v15 dst_sel:WORD_1 dst_unused:UNUSED_PAD src0_sel:DWORD
	v_cvt_f16_f32_e32 v28, v20
	v_cvt_f16_f32_sdwa v29, v21 dst_sel:WORD_1 dst_unused:UNUSED_PAD src0_sel:DWORD
	v_cvt_f16_f32_e32 v30, v22
	v_cvt_f16_f32_sdwa v31, v23 dst_sel:WORD_1 dst_unused:UNUSED_PAD src0_sel:DWORD
	v_ashrrev_i32_e32 v41, 31, v40
	v_or_b32_e32 v24, v25, v24
	v_or_b32_e32 v25, v27, v26
	v_or_b32_e32 v26, v29, v28
	v_or_b32_e32 v27, v31, v30
	v_lshl_add_u64 v[28:29], v[40:41], 4, s[6:7]
	global_store_dwordx4 v[28:29], v[24:27], off sc1
	s_branch .LBB0_24

.LBB0_96:
	s_ashr_i32 s4, s85, 5
	s_ashr_i32 s5, s4, 31
	s_lshl_b64 s[4:5], s[4:5], 23
	s_add_u32 s1, s10, s4
	v_lshl_add_u32 v130, s18, 8, v144
	s_addc_u32 s3, s11, s5
	s_lshl_b32 s0, s0, 20
	v_lshl_or_b32 v128, s19, 8, v145
	v_ashrrev_i32_e32 v131, 31, v130
	s_and_b32 s0, s0, 0x300000
	v_or_b32_e32 v132, s23, v128
	v_lshlrev_b64 v[128:129], 11, v[130:131]
	v_cvt_f16_f32_e32 v124, v124
	v_cvt_f16_f32_sdwa v125, v125 dst_sel:WORD_1 dst_unused:UNUSED_PAD src0_sel:DWORD
	v_cvt_f16_f32_e32 v126, v126
	v_cvt_f16_f32_sdwa v127, v127 dst_sel:WORD_1 dst_unused:UNUSED_PAD src0_sel:DWORD
	v_cvt_f16_f32_e32 v131, v120
	v_cvt_f16_f32_sdwa v134, v121 dst_sel:WORD_1 dst_unused:UNUSED_PAD src0_sel:DWORD
	v_cvt_f16_f32_e32 v135, v122
	v_cvt_f16_f32_sdwa v123, v123 dst_sel:WORD_1 dst_unused:UNUSED_PAD src0_sel:DWORD
	s_add_u32 s0, s1, s0
	s_addc_u32 s1, s3, 0
	v_lshl_add_u64 v[128:129], s[0:1], 0, v[128:129]
	v_lshlrev_b32_e32 v132, 1, v132
	v_mov_b32_e32 v133, 0
	v_lshl_add_u64 v[128:129], v[128:129], 0, v[132:133]
	v_or_b32_e32 v120, v125, v124
	v_or_b32_e32 v121, v127, v126
	v_or_b32_e32 v122, v134, v131
	v_or_b32_e32 v123, v123, v135
	global_store_dwordx4 v[128:129], v[120:123], off sc1
	v_cvt_f16_f32_e32 v116, v116
	v_cvt_f16_f32_sdwa v117, v117 dst_sel:WORD_1 dst_unused:UNUSED_PAD src0_sel:DWORD
	v_cvt_f16_f32_e32 v118, v118
	v_cvt_f16_f32_sdwa v119, v119 dst_sel:WORD_1 dst_unused:UNUSED_PAD src0_sel:DWORD
	v_cvt_f16_f32_e32 v120, v108
	v_cvt_f16_f32_sdwa v121, v109 dst_sel:WORD_1 dst_unused:UNUSED_PAD src0_sel:DWORD
	v_cvt_f16_f32_e32 v122, v110
	v_cvt_f16_f32_sdwa v111, v111 dst_sel:WORD_1 dst_unused:UNUSED_PAD src0_sel:DWORD
	v_or_b32_e32 v108, v117, v116
	v_or_b32_e32 v109, v119, v118
	v_or_b32_e32 v110, v121, v120
	v_or_b32_e32 v111, v111, v122
	global_store_dwordx4 v[128:129], v[108:111], off offset:256 sc1
	v_cvt_f16_f32_e32 v116, v106
	v_cvt_f16_f32_sdwa v107, v107 dst_sel:WORD_1 dst_unused:UNUSED_PAD src0_sel:DWORD
	v_or_b32_e32 v108, 16, v130
	v_cvt_f16_f32_e32 v110, v112
	v_cvt_f16_f32_sdwa v111, v113 dst_sel:WORD_1 dst_unused:UNUSED_PAD src0_sel:DWORD
	v_cvt_f16_f32_e32 v112, v114
	v_cvt_f16_f32_sdwa v113, v115 dst_sel:WORD_1 dst_unused:UNUSED_PAD src0_sel:DWORD
	v_cvt_f16_f32_e32 v114, v104
	v_cvt_f16_f32_sdwa v115, v105 dst_sel:WORD_1 dst_unused:UNUSED_PAD src0_sel:DWORD
	v_ashrrev_i32_e32 v109, 31, v108
	v_lshlrev_b64 v[108:109], 11, v[108:109]
	v_lshl_add_u64 v[108:109], s[0:1], 0, v[108:109]
	v_lshl_add_u64 v[108:109], v[108:109], 0, v[132:133]
	v_or_b32_e32 v104, v111, v110
	v_or_b32_e32 v105, v113, v112
	v_or_b32_e32 v106, v115, v114
	v_or_b32_e32 v107, v107, v116
	global_store_dwordx4 v[108:109], v[104:107], off sc1
	v_cvt_f16_f32_e32 v100, v100
	v_cvt_f16_f32_sdwa v101, v101 dst_sel:WORD_1 dst_unused:UNUSED_PAD src0_sel:DWORD
	v_cvt_f16_f32_e32 v102, v102
	v_cvt_f16_f32_sdwa v103, v103 dst_sel:WORD_1 dst_unused:UNUSED_PAD src0_sel:DWORD
	v_cvt_f16_f32_e32 v104, v92
	v_cvt_f16_f32_sdwa v105, v93 dst_sel:WORD_1 dst_unused:UNUSED_PAD src0_sel:DWORD
	v_cvt_f16_f32_e32 v106, v94
	v_cvt_f16_f32_sdwa v95, v95 dst_sel:WORD_1 dst_unused:UNUSED_PAD src0_sel:DWORD
	v_or_b32_e32 v92, v101, v100
	v_or_b32_e32 v93, v103, v102
	v_or_b32_e32 v94, v105, v104
	v_or_b32_e32 v95, v95, v106
	global_store_dwordx4 v[108:109], v[92:95], off offset:256 sc1
	v_cvt_f16_f32_e32 v100, v90
	v_cvt_f16_f32_sdwa v91, v91 dst_sel:WORD_1 dst_unused:UNUSED_PAD src0_sel:DWORD
	v_or_b32_e32 v92, 32, v130
	v_cvt_f16_f32_e32 v94, v96
	v_cvt_f16_f32_sdwa v95, v97 dst_sel:WORD_1 dst_unused:UNUSED_PAD src0_sel:DWORD
	v_cvt_f16_f32_e32 v96, v98
	v_cvt_f16_f32_sdwa v97, v99 dst_sel:WORD_1 dst_unused:UNUSED_PAD src0_sel:DWORD
	v_cvt_f16_f32_e32 v98, v88
	v_cvt_f16_f32_sdwa v99, v89 dst_sel:WORD_1 dst_unused:UNUSED_PAD src0_sel:DWORD
	v_ashrrev_i32_e32 v93, 31, v92
	v_lshlrev_b64 v[92:93], 11, v[92:93]
	v_lshl_add_u64 v[92:93], s[0:1], 0, v[92:93]
	v_lshl_add_u64 v[92:93], v[92:93], 0, v[132:133]
	v_or_b32_e32 v88, v95, v94
	v_or_b32_e32 v89, v97, v96
	v_or_b32_e32 v90, v99, v98
	v_or_b32_e32 v91, v91, v100
	global_store_dwordx4 v[92:93], v[88:91], off sc1
	v_cvt_f16_f32_e32 v84, v84
	v_cvt_f16_f32_sdwa v85, v85 dst_sel:WORD_1 dst_unused:UNUSED_PAD src0_sel:DWORD
	v_cvt_f16_f32_e32 v86, v86
	v_cvt_f16_f32_sdwa v87, v87 dst_sel:WORD_1 dst_unused:UNUSED_PAD src0_sel:DWORD
	v_cvt_f16_f32_e32 v88, v76
	v_cvt_f16_f32_sdwa v89, v77 dst_sel:WORD_1 dst_unused:UNUSED_PAD src0_sel:DWORD
	v_cvt_f16_f32_e32 v90, v78
	v_cvt_f16_f32_sdwa v79, v79 dst_sel:WORD_1 dst_unused:UNUSED_PAD src0_sel:DWORD
	v_or_b32_e32 v76, v85, v84
	v_or_b32_e32 v77, v87, v86
	v_or_b32_e32 v78, v89, v88
	v_or_b32_e32 v79, v79, v90
	global_store_dwordx4 v[92:93], v[76:79], off offset:256 sc1
	v_cvt_f16_f32_e32 v84, v74
	v_cvt_f16_f32_sdwa v75, v75 dst_sel:WORD_1 dst_unused:UNUSED_PAD src0_sel:DWORD
	v_or_b32_e32 v76, 48, v130
	v_cvt_f16_f32_e32 v78, v80
	v_cvt_f16_f32_sdwa v79, v81 dst_sel:WORD_1 dst_unused:UNUSED_PAD src0_sel:DWORD
	v_cvt_f16_f32_e32 v80, v82
	v_cvt_f16_f32_sdwa v81, v83 dst_sel:WORD_1 dst_unused:UNUSED_PAD src0_sel:DWORD
	v_cvt_f16_f32_e32 v82, v72
	v_cvt_f16_f32_sdwa v83, v73 dst_sel:WORD_1 dst_unused:UNUSED_PAD src0_sel:DWORD
	v_ashrrev_i32_e32 v77, 31, v76
	v_lshlrev_b64 v[76:77], 11, v[76:77]
	v_lshl_add_u64 v[76:77], s[0:1], 0, v[76:77]
	v_lshl_add_u64 v[76:77], v[76:77], 0, v[132:133]
	v_or_b32_e32 v72, v79, v78
	v_or_b32_e32 v73, v81, v80
	v_or_b32_e32 v74, v83, v82
	v_or_b32_e32 v75, v75, v84
	global_store_dwordx4 v[76:77], v[72:75], off sc1
	v_cvt_f16_f32_e32 v68, v68
	v_cvt_f16_f32_sdwa v69, v69 dst_sel:WORD_1 dst_unused:UNUSED_PAD src0_sel:DWORD
	v_cvt_f16_f32_e32 v70, v70
	v_cvt_f16_f32_sdwa v71, v71 dst_sel:WORD_1 dst_unused:UNUSED_PAD src0_sel:DWORD
	v_cvt_f16_f32_e32 v72, v64
	v_cvt_f16_f32_sdwa v73, v65 dst_sel:WORD_1 dst_unused:UNUSED_PAD src0_sel:DWORD
	v_cvt_f16_f32_e32 v74, v66
	v_cvt_f16_f32_sdwa v67, v67 dst_sel:WORD_1 dst_unused:UNUSED_PAD src0_sel:DWORD
	v_or_b32_e32 v64, v69, v68
	v_or_b32_e32 v65, v71, v70
	v_or_b32_e32 v66, v73, v72
	v_or_b32_e32 v67, v67, v74
	v_cvt_f16_f32_e32 v60, v60
	v_cvt_f16_f32_sdwa v61, v61 dst_sel:WORD_1 dst_unused:UNUSED_PAD src0_sel:DWORD
	global_store_dwordx4 v[76:77], v[64:67], off offset:256 sc1
	v_cvt_f16_f32_e32 v62, v62
	v_cvt_f16_f32_sdwa v63, v63 dst_sel:WORD_1 dst_unused:UNUSED_PAD src0_sel:DWORD
	v_cvt_f16_f32_e32 v66, v56
	v_cvt_f16_f32_sdwa v67, v57 dst_sel:WORD_1 dst_unused:UNUSED_PAD src0_sel:DWORD
	v_cvt_f16_f32_e32 v68, v58
	v_cvt_f16_f32_sdwa v59, v59 dst_sel:WORD_1 dst_unused:UNUSED_PAD src0_sel:DWORD
	s_mov_b64 s[0:1], 0x40000
	v_lshl_add_u64 v[64:65], v[128:129], 0, s[0:1]
	s_mov_b32 s0, 0x40000
	v_or_b32_e32 v56, v61, v60
	v_add_co_u32_e32 v60, vcc, s0, v128
	v_or_b32_e32 v57, v63, v62
	v_or_b32_e32 v58, v67, v66
	v_or_b32_e32 v59, v59, v68
	v_addc_co_u32_e32 v61, vcc, 0, v129, vcc
	global_store_dwordx4 v[60:61], v[56:59], off sc1
	v_cvt_f16_f32_e32 v48, v48
	v_cvt_f16_f32_sdwa v49, v49 dst_sel:WORD_1 dst_unused:UNUSED_PAD src0_sel:DWORD
	v_cvt_f16_f32_e32 v50, v50
	v_cvt_f16_f32_sdwa v51, v51 dst_sel:WORD_1 dst_unused:UNUSED_PAD src0_sel:DWORD
	v_cvt_f16_f32_e32 v56, v40
	v_cvt_f16_f32_sdwa v57, v41 dst_sel:WORD_1 dst_unused:UNUSED_PAD src0_sel:DWORD
	v_cvt_f16_f32_e32 v58, v42
	v_cvt_f16_f32_sdwa v43, v43 dst_sel:WORD_1 dst_unused:UNUSED_PAD src0_sel:DWORD
	v_or_b32_e32 v40, v49, v48
	v_or_b32_e32 v41, v51, v50
	v_or_b32_e32 v42, v57, v56
	v_or_b32_e32 v43, v43, v58
	global_store_dwordx4 v[64:65], v[40:43], off offset:256 sc1
	v_cvt_f16_f32_e32 v44, v44
	v_cvt_f16_f32_sdwa v45, v45 dst_sel:WORD_1 dst_unused:UNUSED_PAD src0_sel:DWORD
	v_cvt_f16_f32_e32 v40, v52
	v_cvt_f16_f32_sdwa v41, v53 dst_sel:WORD_1 dst_unused:UNUSED_PAD src0_sel:DWORD
	v_cvt_f16_f32_e32 v42, v54
	v_cvt_f16_f32_sdwa v43, v55 dst_sel:WORD_1 dst_unused:UNUSED_PAD src0_sel:DWORD
	v_cvt_f16_f32_e32 v46, v46
	v_cvt_f16_f32_sdwa v47, v47 dst_sel:WORD_1 dst_unused:UNUSED_PAD src0_sel:DWORD
	s_mov_b64 s[0:1], 0x48000
	v_lshl_add_u64 v[48:49], v[128:129], 0, s[0:1]
	s_mov_b32 s0, 0x48000
	v_or_b32_e32 v40, v41, v40
	v_or_b32_e32 v41, v43, v42
	v_or_b32_e32 v42, v45, v44
	v_add_co_u32_e32 v44, vcc, s0, v128
	v_or_b32_e32 v43, v47, v46
	s_nop 0
	v_addc_co_u32_e32 v45, vcc, 0, v129, vcc
	global_store_dwordx4 v[44:45], v[40:43], off sc1
	v_cvt_f16_f32_e32 v32, v32
	v_cvt_f16_f32_sdwa v33, v33 dst_sel:WORD_1 dst_unused:UNUSED_PAD src0_sel:DWORD
	v_cvt_f16_f32_e32 v34, v34
	v_cvt_f16_f32_sdwa v35, v35 dst_sel:WORD_1 dst_unused:UNUSED_PAD src0_sel:DWORD
	v_cvt_f16_f32_e32 v40, v24
	v_cvt_f16_f32_sdwa v41, v25 dst_sel:WORD_1 dst_unused:UNUSED_PAD src0_sel:DWORD
	v_cvt_f16_f32_e32 v42, v26
	v_cvt_f16_f32_sdwa v27, v27 dst_sel:WORD_1 dst_unused:UNUSED_PAD src0_sel:DWORD
	v_or_b32_e32 v24, v33, v32
	v_or_b32_e32 v25, v35, v34
	v_or_b32_e32 v26, v41, v40
	v_or_b32_e32 v27, v27, v42
	global_store_dwordx4 v[48:49], v[24:27], off offset:256 sc1
	v_cvt_f16_f32_e32 v28, v28
	v_cvt_f16_f32_sdwa v29, v29 dst_sel:WORD_1 dst_unused:UNUSED_PAD src0_sel:DWORD
	v_cvt_f16_f32_e32 v24, v36
	v_cvt_f16_f32_sdwa v25, v37 dst_sel:WORD_1 dst_unused:UNUSED_PAD src0_sel:DWORD
	v_cvt_f16_f32_e32 v26, v38
	v_cvt_f16_f32_sdwa v27, v39 dst_sel:WORD_1 dst_unused:UNUSED_PAD src0_sel:DWORD
	v_cvt_f16_f32_e32 v30, v30
	v_cvt_f16_f32_sdwa v31, v31 dst_sel:WORD_1 dst_unused:UNUSED_PAD src0_sel:DWORD
	s_mov_b64 s[0:1], 0x50000
	v_lshl_add_u64 v[32:33], v[128:129], 0, s[0:1]
	s_mov_b32 s0, 0x50000
	v_or_b32_e32 v24, v25, v24
	v_or_b32_e32 v25, v27, v26
	v_or_b32_e32 v26, v29, v28
	v_add_co_u32_e32 v28, vcc, s0, v128
	v_or_b32_e32 v27, v31, v30
	s_nop 0
	v_addc_co_u32_e32 v29, vcc, 0, v129, vcc
	global_store_dwordx4 v[28:29], v[24:27], off sc1
	v_cvt_f16_f32_e32 v16, v16
	v_cvt_f16_f32_sdwa v17, v17 dst_sel:WORD_1 dst_unused:UNUSED_PAD src0_sel:DWORD
	v_cvt_f16_f32_e32 v18, v18
	v_cvt_f16_f32_sdwa v19, v19 dst_sel:WORD_1 dst_unused:UNUSED_PAD src0_sel:DWORD
	v_cvt_f16_f32_e32 v24, v8
	v_cvt_f16_f32_sdwa v25, v9 dst_sel:WORD_1 dst_unused:UNUSED_PAD src0_sel:DWORD
	v_cvt_f16_f32_e32 v26, v10
	v_cvt_f16_f32_sdwa v11, v11 dst_sel:WORD_1 dst_unused:UNUSED_PAD src0_sel:DWORD
	v_or_b32_e32 v8, v17, v16
	v_or_b32_e32 v9, v19, v18
	v_or_b32_e32 v10, v25, v24
	v_or_b32_e32 v11, v11, v26
	global_store_dwordx4 v[32:33], v[8:11], off offset:256 sc1
	v_cvt_f16_f32_e32 v12, v12
	v_cvt_f16_f32_sdwa v13, v13 dst_sel:WORD_1 dst_unused:UNUSED_PAD src0_sel:DWORD
	v_cvt_f16_f32_e32 v8, v20
	v_cvt_f16_f32_sdwa v9, v21 dst_sel:WORD_1 dst_unused:UNUSED_PAD src0_sel:DWORD
	v_cvt_f16_f32_e32 v10, v22
	v_cvt_f16_f32_sdwa v11, v23 dst_sel:WORD_1 dst_unused:UNUSED_PAD src0_sel:DWORD
	v_cvt_f16_f32_e32 v14, v14
	v_cvt_f16_f32_sdwa v15, v15 dst_sel:WORD_1 dst_unused:UNUSED_PAD src0_sel:DWORD
	s_mov_b64 s[0:1], 0x58000
	v_lshl_add_u64 v[16:17], v[128:129], 0, s[0:1]
	s_mov_b32 s0, 0x58000
	v_or_b32_e32 v8, v9, v8
	v_or_b32_e32 v9, v11, v10
	v_or_b32_e32 v10, v13, v12
	v_add_co_u32_e32 v12, vcc, s0, v128
	v_or_b32_e32 v11, v15, v14
	s_nop 0
	v_addc_co_u32_e32 v13, vcc, 0, v129, vcc
	global_store_dwordx4 v[12:13], v[8:11], off sc1
	v_cvt_f16_f32_e32 v4, v4
	v_cvt_f16_f32_sdwa v5, v5 dst_sel:WORD_1 dst_unused:UNUSED_PAD src0_sel:DWORD
	v_cvt_f16_f32_e32 v6, v6
	v_cvt_f16_f32_sdwa v7, v7 dst_sel:WORD_1 dst_unused:UNUSED_PAD src0_sel:DWORD
	v_cvt_f16_f32_e32 v8, v0
	v_cvt_f16_f32_sdwa v9, v1 dst_sel:WORD_1 dst_unused:UNUSED_PAD src0_sel:DWORD
	v_cvt_f16_f32_e32 v10, v2
	v_cvt_f16_f32_sdwa v3, v3 dst_sel:WORD_1 dst_unused:UNUSED_PAD src0_sel:DWORD
	v_or_b32_e32 v0, v5, v4
	v_or_b32_e32 v1, v7, v6
	v_or_b32_e32 v2, v9, v8
	v_or_b32_e32 v3, v3, v10
	global_store_dwordx4 v[16:17], v[0:3], off offset:256 sc1
	s_waitcnt vmcnt(0)
	s_barrier

.LBB0_99:
	s_waitcnt lgkmcnt(0)
	s_barrier
	ds_read2_b32 v[18:19], v15 offset1:65
	s_ashr_i32 s13, s12, 31
	s_lshr_b32 s13, s13, 23
	s_add_i32 s13, s12, s13
	ds_read2_b32 v[20:21], v15 offset0:130 offset1:195
	s_waitcnt lgkmcnt(1)
	v_cvt_f16_f32_e32 v11, v18
	v_add_u32_e32 v18, 0x400, v15
	ds_read2_b32 v[22:23], v18 offset0:4 offset1:69
	s_ashr_i32 s14, s13, 9
	s_and_b32 s13, s13, 0xfe00
	s_sub_i32 s12, s12, s13
	s_sext_i32_i16 s13, s12
	s_bfe_u32 s13, s13, 0x5001a
	v_cvt_f16_f32_sdwa v24, v19 dst_sel:WORD_1 dst_unused:UNUSED_PAD src0_sel:DWORD
	ds_read2_b32 v[18:19], v18 offset0:134 offset1:199
	s_add_i32 s13, s12, s13
	s_waitcnt lgkmcnt(2)
	v_cvt_f16_f32_e32 v20, v20
	v_cvt_f16_f32_sdwa v21, v21 dst_sel:WORD_1 dst_unused:UNUSED_PAD src0_sel:DWORD
	s_waitcnt lgkmcnt(1)
	v_cvt_f16_f32_e32 v22, v22
	v_cvt_f16_f32_sdwa v23, v23 dst_sel:WORD_1 dst_unused:UNUSED_PAD src0_sel:DWORD
	s_sext_i32_i16 s16, s13
	s_and_b32 s13, s13, 0xffe0
	s_sub_i32 s12, s12, s13
	s_sext_i32_i16 s17, s12
	s_ashr_i32 s15, s14, 31
	s_lshl_b64 s[12:13], s[14:15], 23
	s_waitcnt lgkmcnt(0)
	v_cvt_f16_f32_sdwa v26, v19 dst_sel:WORD_1 dst_unused:UNUSED_PAD src0_sel:DWORD
	v_or_b32_e32 v19, v21, v20
	v_or_b32_e32 v20, v23, v22
	v_lshl_add_u32 v22, s17, 6, v14
	s_add_u32 s12, s3, s12
	v_ashrrev_i32_e32 v23, 31, v22
	s_addc_u32 s13, s6, s13
	v_lshlrev_b64 v[22:23], 11, v[22:23]
	v_cvt_f16_f32_e32 v25, v18
	v_lshl_add_u64 v[22:23], s[12:13], 0, v[22:23]
	s_lshl_b32 s12, s16, 1
	s_andn2_b32 s12, s12, 63
	s_ashr_i32 s13, s12, 31
	v_lshl_add_u64 v[22:23], s[12:13], 1, v[22:23]
	v_or_b32_e32 v18, v24, v11
	v_or_b32_e32 v21, v26, v25
	v_lshl_add_u64 v[22:23], v[22:23], 0, v[8:9]
	s_andn2_b64 vcc, exec, s[4:5]
	s_mov_b32 s12, s9
	global_store_dwordx4 v[22:23], v[18:21], off sc1
	s_barrier
	s_cbranch_vccz .LBB0_102

.LBB0_104:
	s_ashr_i32 s5, s4, 31
	s_lshr_b32 s5, s5, 23
	s_add_i32 s5, s4, s5
	s_ashr_i32 s6, s5, 9
	s_and_b32 s5, s5, 0xfe00
	s_sub_i32 s4, s4, s5
	s_sext_i32_i16 s5, s4
	s_waitcnt lgkmcnt(0)
	s_barrier
	s_bfe_u32 s5, s5, 0x4001b
	ds_read2_b32 v[18:19], v15 offset1:65
	ds_read2_b32 v[20:21], v15 offset0:130 offset1:195
	v_add_u32_e32 v11, 0x400, v15
	s_add_i32 s5, s4, s5
	ds_read2_b32 v[22:23], v11 offset0:4 offset1:69
	ds_read2_b32 v[24:25], v11 offset0:134 offset1:199
	s_sext_i32_i16 s12, s5
	s_and_b32 s5, s5, 0xfff0
	s_sub_i32 s4, s4, s5
	s_sext_i32_i16 s13, s4
	s_ashr_i32 s7, s6, 31
	s_lshl_b64 s[4:5], s[6:7], 22
	s_waitcnt lgkmcnt(3)
	v_cvt_pk_bf16_f32 v18, v18, v19
	s_waitcnt lgkmcnt(2)
	v_cvt_pk_bf16_f32 v19, v20, v21
	s_waitcnt lgkmcnt(1)
	v_cvt_pk_bf16_f32 v20, v22, v23
	v_lshl_add_u32 v22, s13, 6, v14
	s_add_u32 s4, s64, s4
	v_ashrrev_i32_e32 v23, 31, v22
	s_addc_u32 s5, s65, s5
	v_lshlrev_b64 v[22:23], 12, v[22:23]
	v_lshl_add_u64 v[22:23], s[4:5], 0, v[22:23]
	s_lshl_b32 s4, s12, 2
	s_andn2_b32 s4, s4, 63
	s_ashr_i32 s5, s4, 31
	v_lshl_add_u64 v[22:23], s[4:5], 1, v[22:23]
	s_waitcnt lgkmcnt(0)
	v_cvt_pk_bf16_f32 v21, v24, v25
	v_lshl_add_u64 v[22:23], v[22:23], 0, v[8:9]
	s_andn2_b64 vcc, exec, s[0:1]
	s_mov_b32 s4, s3
	global_store_dwordx4 v[22:23], v[18:21], off sc1
	s_barrier
	s_cbranch_vccz .LBB0_107

.LBB0_109:
	s_mul_hi_i32 s6, s5, 0x2aaaaaab
	s_lshr_b32 s7, s6, 31
	s_lshr_b32 s6, s6, 8
	s_waitcnt lgkmcnt(0)
	s_barrier
	s_add_i32 s6, s6, s7
	ds_read2_b32 v[20:21], v15 offset1:65
	s_mulk_i32 s6, 0x600
	ds_read2_b32 v[22:23], v15 offset0:130 offset1:195
	ds_read2_b32 v[24:25], v18 offset0:4 offset1:69
	s_sub_i32 s5, s5, s6
	s_sext_i32_i16 s6, s5
	s_mulk_i32 s6, 0x2aab
	s_lshr_b32 s7, s6, 31
	s_ashr_i32 s6, s6, 20
	s_waitcnt lgkmcnt(2)
	v_cvt_f16_f32_e32 v19, v20
	v_cvt_f16_f32_sdwa v26, v21 dst_sel:WORD_1 dst_unused:UNUSED_PAD src0_sel:DWORD
	ds_read2_b32 v[20:21], v18 offset0:134 offset1:199
	s_add_i32 s6, s6, s7
	s_waitcnt lgkmcnt(2)
	v_cvt_f16_f32_e32 v22, v22
	v_cvt_f16_f32_sdwa v23, v23 dst_sel:WORD_1 dst_unused:UNUSED_PAD src0_sel:DWORD
	s_waitcnt lgkmcnt(1)
	v_cvt_f16_f32_e32 v24, v24
	v_cvt_f16_f32_sdwa v25, v25 dst_sel:WORD_1 dst_unused:UNUSED_PAD src0_sel:DWORD
	s_sext_i32_i16 s7, s6
	s_mulk_i32 s6, 0x60
	s_sub_i32 s5, s5, s6
	s_sext_i32_i16 s5, s5
	s_waitcnt lgkmcnt(0)
	v_cvt_f16_f32_sdwa v28, v21 dst_sel:WORD_1 dst_unused:UNUSED_PAD src0_sel:DWORD
	v_or_b32_e32 v21, v23, v22
	v_or_b32_e32 v22, v25, v24
	v_lshl_add_u32 v24, s5, 6, v14
	v_cvt_f16_f32_e32 v27, v20
	v_ashrrev_i32_e32 v25, 31, v24
	v_readlane_b32 s12, v252, 22
	v_lshlrev_b64 v[24:25], 11, v[24:25]
	v_readlane_b32 s13, v252, 23
	s_lshl_b32 s6, s7, 6
	s_ashr_i32 s7, s6, 31
	v_lshl_add_u64 v[24:25], s[12:13], 0, v[24:25]
	v_lshl_add_u64 v[24:25], s[6:7], 1, v[24:25]
	v_or_b32_e32 v20, v26, v19
	v_or_b32_e32 v23, v28, v27
	v_lshl_add_u64 v[24:25], v[24:25], 0, v[8:9]
	s_andn2_b64 vcc, exec, s[0:1]
	s_mov_b32 s5, s4
	global_store_dwordx4 v[24:25], v[20:23], off sc1
	s_barrier
	s_cbranch_vccz .LBB0_112

.LBB0_114:
	s_waitcnt lgkmcnt(0)
	s_barrier
	ds_read2_b32 v[18:19], v15 offset1:65
	s_ashr_i32 s5, s4, 31
	s_lshr_b32 s5, s5, 22
	s_add_i32 s5, s4, s5
	ds_read2_b32 v[20:21], v15 offset0:130 offset1:195
	s_waitcnt lgkmcnt(1)
	v_cvt_f16_f32_e32 v11, v18
	v_add_u32_e32 v18, 0x400, v15
	ds_read2_b32 v[22:23], v18 offset0:4 offset1:69
	s_ashr_i32 s6, s5, 10
	s_and_b32 s5, s5, 0xfc00
	s_sub_i32 s4, s4, s5
	s_sext_i32_i16 s5, s4
	s_bfe_u32 s5, s5, 0x60019
	v_cvt_f16_f32_sdwa v24, v19 dst_sel:WORD_1 dst_unused:UNUSED_PAD src0_sel:DWORD
	ds_read2_b32 v[18:19], v18 offset0:134 offset1:199
	s_add_i32 s5, s4, s5
	s_waitcnt lgkmcnt(2)
	v_cvt_f16_f32_e32 v20, v20
	v_cvt_f16_f32_sdwa v21, v21 dst_sel:WORD_1 dst_unused:UNUSED_PAD src0_sel:DWORD
	s_waitcnt lgkmcnt(1)
	v_cvt_f16_f32_e32 v22, v22
	v_cvt_f16_f32_sdwa v23, v23 dst_sel:WORD_1 dst_unused:UNUSED_PAD src0_sel:DWORD
	s_sext_i32_i16 s12, s5
	s_and_b32 s5, s5, 0xffc0
	s_sub_i32 s4, s4, s5
	s_sext_i32_i16 s13, s4
	s_ashr_i32 s7, s6, 31
	s_lshl_b64 s[4:5], s[6:7], 23
	v_readlane_b32 s6, v252, 24
	s_waitcnt lgkmcnt(0)
	v_cvt_f16_f32_sdwa v26, v19 dst_sel:WORD_1 dst_unused:UNUSED_PAD src0_sel:DWORD
	v_or_b32_e32 v19, v21, v20
	v_or_b32_e32 v20, v23, v22
	v_lshl_add_u32 v22, s13, 6, v14
	s_add_u32 s4, s6, s4
	v_readlane_b32 s6, v252, 25
	v_ashrrev_i32_e32 v23, 31, v22
	s_addc_u32 s5, s6, s5
	v_cvt_f16_f32_e32 v25, v18
	v_lshlrev_b64 v[22:23], 11, v[22:23]
	v_lshl_add_u64 v[22:23], s[4:5], 0, v[22:23]
	s_and_b32 s4, s12, 0xffffffc0
	s_ashr_i32 s5, s4, 31
	v_lshl_add_u64 v[22:23], s[4:5], 1, v[22:23]
	v_or_b32_e32 v18, v24, v11
	v_or_b32_e32 v21, v26, v25
	v_lshl_add_u64 v[22:23], v[22:23], 0, v[8:9]
	s_andn2_b64 vcc, exec, s[0:1]
	s_mov_b32 s4, s3
	global_store_dwordx4 v[22:23], v[18:21], off sc1
	s_barrier
	s_cbranch_vccz .LBB0_117

.LBB0_127:
	s_or_b64 exec, exec, s[18:19]
	s_waitcnt vmcnt(0)
	v_cvt_f16_f32_e32 v28, v28
	v_cvt_f16_f32_sdwa v29, v29 dst_sel:WORD_1 dst_unused:UNUSED_PAD src0_sel:DWORD
	v_cvt_f16_f32_e32 v30, v30
	v_cvt_f16_f32_sdwa v31, v31 dst_sel:WORD_1 dst_unused:UNUSED_PAD src0_sel:DWORD
	v_cvt_f16_f32_e32 v41, v24
	v_cvt_f16_f32_sdwa v42, v25 dst_sel:WORD_1 dst_unused:UNUSED_PAD src0_sel:DWORD
	v_cvt_f16_f32_e32 v43, v26
	v_cvt_f16_f32_sdwa v27, v27 dst_sel:WORD_1 dst_unused:UNUSED_PAD src0_sel:DWORD
	v_or_b32_e32 v24, v29, v28
	v_or_b32_e32 v25, v31, v30
	v_or_b32_e32 v26, v42, v41
	v_or_b32_e32 v27, v27, v43
	v_lshl_add_u64 v[28:29], v[32:33], 4, s[28:29]
	global_store_dwordx4 v[28:29], v[24:27], off sc1
	s_and_saveexec_b64 s[18:19], vcc
	s_cbranch_execnz .LBB0_130
	s_or_b64 exec, exec, s[18:19]
	s_and_saveexec_b64 s[18:19], s[0:1]
	s_cbranch_execnz .LBB0_131

.LBB0_130:
	v_cvt_f16_f32_e32 v24, v0
	v_cvt_f16_f32_sdwa v25, v1 dst_sel:WORD_1 dst_unused:UNUSED_PAD src0_sel:DWORD
	v_cvt_f16_f32_e32 v26, v2
	v_cvt_f16_f32_sdwa v27, v3 dst_sel:WORD_1 dst_unused:UNUSED_PAD src0_sel:DWORD
	v_cvt_f16_f32_e32 v28, v8
	v_cvt_f16_f32_sdwa v29, v9 dst_sel:WORD_1 dst_unused:UNUSED_PAD src0_sel:DWORD
	v_cvt_f16_f32_e32 v30, v10
	v_cvt_f16_f32_sdwa v31, v11 dst_sel:WORD_1 dst_unused:UNUSED_PAD src0_sel:DWORD
	v_or_b32_e32 v24, v25, v24
	v_or_b32_e32 v25, v27, v26
	v_or_b32_e32 v26, v29, v28
	v_or_b32_e32 v27, v31, v30
	v_lshl_add_u64 v[28:29], v[34:35], 4, s[28:29]
	global_store_dwordx4 v[28:29], v[24:27], off sc1
	s_or_b64 exec, exec, s[18:19]
	s_and_saveexec_b64 s[18:19], s[0:1]
	s_cbranch_execz .LBB0_129
.LBB0_131:
	v_cvt_f16_f32_e32 v24, v4
	v_cvt_f16_f32_sdwa v25, v5 dst_sel:WORD_1 dst_unused:UNUSED_PAD src0_sel:DWORD
	v_cvt_f16_f32_e32 v26, v6
	v_cvt_f16_f32_sdwa v27, v7 dst_sel:WORD_1 dst_unused:UNUSED_PAD src0_sel:DWORD
	v_cvt_f16_f32_e32 v28, v16
	v_cvt_f16_f32_sdwa v29, v17 dst_sel:WORD_1 dst_unused:UNUSED_PAD src0_sel:DWORD
	v_cvt_f16_f32_e32 v30, v18
	v_cvt_f16_f32_sdwa v31, v19 dst_sel:WORD_1 dst_unused:UNUSED_PAD src0_sel:DWORD
	v_or_b32_e32 v24, v25, v24
	v_or_b32_e32 v25, v27, v26
	v_or_b32_e32 v26, v29, v28
	v_or_b32_e32 v27, v31, v30
	v_lshl_add_u64 v[28:29], v[36:37], 4, s[28:29]
	global_store_dwordx4 v[28:29], v[24:27], off sc1
	s_or_b64 exec, exec, s[18:19]
	s_and_saveexec_b64 s[0:1], s[4:5]
	s_cbranch_execz .LBB0_120
.LBB0_132:
	v_cvt_f16_f32_e32 v24, v12
	v_cvt_f16_f32_sdwa v25, v13 dst_sel:WORD_1 dst_unused:UNUSED_PAD src0_sel:DWORD
	v_cvt_f16_f32_e32 v26, v14
	v_cvt_f16_f32_sdwa v27, v15 dst_sel:WORD_1 dst_unused:UNUSED_PAD src0_sel:DWORD
	v_cvt_f16_f32_e32 v28, v20
	v_cvt_f16_f32_sdwa v29, v21 dst_sel:WORD_1 dst_unused:UNUSED_PAD src0_sel:DWORD
	v_cvt_f16_f32_e32 v30, v22
	v_cvt_f16_f32_sdwa v31, v23 dst_sel:WORD_1 dst_unused:UNUSED_PAD src0_sel:DWORD
	v_or_b32_e32 v24, v25, v24
	v_or_b32_e32 v25, v27, v26
	v_or_b32_e32 v26, v29, v28
	v_or_b32_e32 v27, v31, v30
	v_lshl_add_u64 v[28:29], v[38:39], 4, s[28:29]
	global_store_dwordx4 v[28:29], v[24:27], off sc1
	s_branch .LBB0_120
